# attention: static s_setprio 1 for map-1 waves instead of the per-step sleep stagger
# baseline (speedup 1.0000x reference)
.LBB0_310:
	s_and_b64 vcc, exec, s[40:41]
	s_cbranch_vccz .Lat_nostag
	s_setprio 1

.LBB0_321:
	s_setprio 0
	v_mov_b32_e32 v0, v207
	s_nop 1
	v_permlane32_swap_b32_e32 v207, v0
	v_add_f32_e32 v0, v207, v0
	v_lshl_add_u32 v2, v206, 2, s76
	s_and_b64 vcc, exec, s[40:41]
	s_barrier
	s_cbranch_vccz .LBB0_323
	v_div_scale_f32 v3, s[4:5], v0, v0, v193
	v_rcp_f32_e32 v4, v3
	v_div_scale_f32 v5, vcc, v193, v0, v193
	v_fma_f32 v6, -v3, v4, 1.0
	v_fmac_f32_e32 v4, v6, v4
	v_mul_f32_e32 v6, v5, v4
	v_fma_f32 v7, -v3, v6, v5
	v_fmac_f32_e32 v6, v7, v4
	v_fma_f32 v3, -v3, v6, v5
	v_div_fmas_f32 v3, v3, v4, v6
	v_div_fixup_f32 v3, v3, v0, v193
	v_mul_f32_e32 v4, v128, v3
	v_mul_f32_e32 v5, v129, v3
	ds_write2st64_b32 v2, v4, v5 offset1:1
	v_mul_f32_e32 v4, v130, v3
	v_mul_f32_e32 v5, v131, v3
	ds_write2st64_b32 v2, v4, v5 offset0:2 offset1:3
	v_mul_f32_e32 v4, v132, v3
	v_mul_f32_e32 v5, v133, v3
	ds_write2st64_b32 v2, v4, v5 offset0:4 offset1:5
	v_mul_f32_e32 v4, v134, v3
	v_mul_f32_e32 v5, v135, v3
	ds_write2st64_b32 v2, v4, v5 offset0:6 offset1:7
	v_mul_f32_e32 v4, v136, v3
	v_mul_f32_e32 v5, v137, v3
	ds_write2st64_b32 v2, v4, v5 offset0:8 offset1:9
	v_mul_f32_e32 v4, v138, v3
	v_mul_f32_e32 v5, v139, v3
	ds_write2st64_b32 v2, v4, v5 offset0:10 offset1:11
	v_mul_f32_e32 v4, v140, v3
	v_mul_f32_e32 v5, v141, v3
	ds_write2st64_b32 v2, v4, v5 offset0:12 offset1:13
	v_mul_f32_e32 v4, v142, v3
	v_mul_f32_e32 v5, v143, v3
	ds_write2st64_b32 v2, v4, v5 offset0:14 offset1:15
	v_mul_f32_e32 v4, v112, v3
	v_mul_f32_e32 v5, v113, v3
	ds_write2st64_b32 v2, v4, v5 offset0:16 offset1:17
	v_mul_f32_e32 v4, v114, v3
	v_mul_f32_e32 v5, v115, v3
	ds_write2st64_b32 v2, v4, v5 offset0:18 offset1:19
	v_mul_f32_e32 v4, v116, v3
	v_mul_f32_e32 v5, v117, v3
	ds_write2st64_b32 v2, v4, v5 offset0:20 offset1:21
	v_mul_f32_e32 v4, v118, v3
	v_mul_f32_e32 v5, v119, v3
	ds_write2st64_b32 v2, v4, v5 offset0:22 offset1:23
	v_mul_f32_e32 v4, v120, v3
	v_mul_f32_e32 v5, v121, v3
	ds_write2st64_b32 v2, v4, v5 offset0:24 offset1:25
	v_mul_f32_e32 v4, v122, v3
	v_mul_f32_e32 v5, v123, v3
	ds_write2st64_b32 v2, v4, v5 offset0:26 offset1:27
	v_mul_f32_e32 v4, v124, v3
	v_mul_f32_e32 v5, v125, v3
	ds_write2st64_b32 v2, v4, v5 offset0:28 offset1:29
	v_mul_f32_e32 v4, v126, v3
	v_mul_f32_e32 v5, v127, v3
	ds_write2st64_b32 v2, v4, v5 offset0:30 offset1:31
	v_mul_f32_e32 v4, v96, v3
	v_mul_f32_e32 v5, v97, v3
	ds_write2st64_b32 v2, v4, v5 offset0:32 offset1:33
	v_mul_f32_e32 v4, v98, v3
	v_mul_f32_e32 v5, v99, v3
	ds_write2st64_b32 v2, v4, v5 offset0:34 offset1:35
	v_mul_f32_e32 v4, v100, v3
	v_mul_f32_e32 v5, v101, v3
	ds_write2st64_b32 v2, v4, v5 offset0:36 offset1:37
	v_mul_f32_e32 v4, v102, v3
	v_mul_f32_e32 v5, v103, v3
	ds_write2st64_b32 v2, v4, v5 offset0:38 offset1:39
	v_mul_f32_e32 v4, v104, v3
	v_mul_f32_e32 v5, v105, v3
	ds_write2st64_b32 v2, v4, v5 offset0:40 offset1:41
	v_mul_f32_e32 v4, v106, v3
	v_mul_f32_e32 v5, v107, v3
	ds_write2st64_b32 v2, v4, v5 offset0:42 offset1:43
	v_mul_f32_e32 v4, v108, v3
	v_mul_f32_e32 v5, v109, v3
	ds_write2st64_b32 v2, v4, v5 offset0:44 offset1:45
	v_mul_f32_e32 v4, v110, v3
	v_mul_f32_e32 v5, v111, v3
	ds_write2st64_b32 v2, v4, v5 offset0:46 offset1:47
	v_mul_f32_e32 v4, v80, v3
	v_mul_f32_e32 v5, v81, v3
	ds_write2st64_b32 v2, v4, v5 offset0:48 offset1:49
	v_mul_f32_e32 v4, v82, v3
	v_mul_f32_e32 v5, v83, v3
	ds_write2st64_b32 v2, v4, v5 offset0:50 offset1:51
	v_mul_f32_e32 v4, v84, v3
	v_mul_f32_e32 v5, v85, v3
	ds_write2st64_b32 v2, v4, v5 offset0:52 offset1:53
	v_mul_f32_e32 v4, v86, v3
	v_mul_f32_e32 v5, v87, v3
	ds_write2st64_b32 v2, v4, v5 offset0:54 offset1:55
	v_mul_f32_e32 v4, v88, v3
	v_mul_f32_e32 v5, v89, v3
	ds_write2st64_b32 v2, v4, v5 offset0:56 offset1:57
	v_mul_f32_e32 v4, v90, v3
	v_mul_f32_e32 v5, v91, v3
	ds_write2st64_b32 v2, v4, v5 offset0:58 offset1:59
	v_mul_f32_e32 v4, v92, v3
	v_mul_f32_e32 v5, v93, v3
	ds_write2st64_b32 v2, v4, v5 offset0:60 offset1:61
	v_mul_f32_e32 v4, v94, v3
	v_mul_f32_e32 v5, v95, v3
	ds_write2st64_b32 v2, v4, v5 offset0:62 offset1:63
	v_mul_f32_e32 v4, v64, v3
	v_mul_f32_e32 v5, v65, v3
	ds_write2st64_b32 v2, v4, v5 offset0:64 offset1:65
	v_mul_f32_e32 v4, v66, v3
	v_mul_f32_e32 v5, v67, v3
	ds_write2st64_b32 v2, v4, v5 offset0:66 offset1:67
	v_mul_f32_e32 v4, v68, v3
	v_mul_f32_e32 v5, v69, v3
	ds_write2st64_b32 v2, v4, v5 offset0:68 offset1:69
	v_mul_f32_e32 v4, v70, v3
	v_mul_f32_e32 v5, v71, v3
	ds_write2st64_b32 v2, v4, v5 offset0:70 offset1:71
	v_mul_f32_e32 v4, v72, v3
	v_mul_f32_e32 v5, v73, v3
	ds_write2st64_b32 v2, v4, v5 offset0:72 offset1:73
	v_mul_f32_e32 v4, v74, v3
	v_mul_f32_e32 v5, v75, v3
	ds_write2st64_b32 v2, v4, v5 offset0:74 offset1:75
	v_mul_f32_e32 v4, v76, v3
	v_mul_f32_e32 v5, v77, v3
	ds_write2st64_b32 v2, v4, v5 offset0:76 offset1:77
	v_mul_f32_e32 v4, v78, v3
	v_mul_f32_e32 v5, v79, v3
	ds_write2st64_b32 v2, v4, v5 offset0:78 offset1:79
	v_mul_f32_e32 v4, v48, v3
	v_mul_f32_e32 v5, v49, v3
	ds_write2st64_b32 v2, v4, v5 offset0:80 offset1:81
	v_mul_f32_e32 v4, v50, v3
	v_mul_f32_e32 v5, v51, v3
	ds_write2st64_b32 v2, v4, v5 offset0:82 offset1:83
	v_mul_f32_e32 v4, v52, v3
	v_mul_f32_e32 v5, v53, v3
	ds_write2st64_b32 v2, v4, v5 offset0:84 offset1:85
	v_mul_f32_e32 v4, v54, v3
	v_mul_f32_e32 v5, v55, v3
	ds_write2st64_b32 v2, v4, v5 offset0:86 offset1:87
	v_mul_f32_e32 v4, v56, v3
	v_mul_f32_e32 v5, v57, v3
	ds_write2st64_b32 v2, v4, v5 offset0:88 offset1:89
	v_mul_f32_e32 v4, v58, v3
	v_mul_f32_e32 v5, v59, v3
	ds_write2st64_b32 v2, v4, v5 offset0:90 offset1:91
	v_mul_f32_e32 v4, v60, v3
	v_mul_f32_e32 v5, v61, v3
	ds_write2st64_b32 v2, v4, v5 offset0:92 offset1:93
	v_mul_f32_e32 v4, v62, v3
	v_mul_f32_e32 v5, v63, v3
	ds_write2st64_b32 v2, v4, v5 offset0:94 offset1:95
	v_mul_f32_e32 v4, v32, v3
	v_mul_f32_e32 v5, v33, v3
	ds_write2st64_b32 v2, v4, v5 offset0:96 offset1:97
	v_mul_f32_e32 v4, v34, v3
	v_mul_f32_e32 v5, v35, v3
	ds_write2st64_b32 v2, v4, v5 offset0:98 offset1:99
	v_mul_f32_e32 v4, v36, v3
	v_mul_f32_e32 v5, v37, v3
	ds_write2st64_b32 v2, v4, v5 offset0:100 offset1:101
	v_mul_f32_e32 v4, v38, v3
	v_mul_f32_e32 v5, v39, v3
	ds_write2st64_b32 v2, v4, v5 offset0:102 offset1:103
	v_mul_f32_e32 v4, v40, v3
	v_mul_f32_e32 v5, v41, v3
	ds_write2st64_b32 v2, v4, v5 offset0:104 offset1:105
	v_mul_f32_e32 v4, v42, v3
	v_mul_f32_e32 v5, v43, v3
	ds_write2st64_b32 v2, v4, v5 offset0:106 offset1:107
	v_mul_f32_e32 v4, v44, v3
	v_mul_f32_e32 v5, v45, v3
	ds_write2st64_b32 v2, v4, v5 offset0:108 offset1:109
	v_mul_f32_e32 v4, v46, v3
	v_mul_f32_e32 v5, v47, v3
	ds_write2st64_b32 v2, v4, v5 offset0:110 offset1:111
	v_mul_f32_e32 v4, v16, v3
	v_mul_f32_e32 v5, v17, v3
	ds_write2st64_b32 v2, v4, v5 offset0:112 offset1:113
	v_mul_f32_e32 v4, v18, v3
	v_mul_f32_e32 v5, v19, v3
	ds_write2st64_b32 v2, v4, v5 offset0:114 offset1:115
	v_mul_f32_e32 v4, v20, v3
	v_mul_f32_e32 v5, v21, v3
	ds_write2st64_b32 v2, v4, v5 offset0:116 offset1:117
	v_mul_f32_e32 v4, v22, v3
	v_mul_f32_e32 v5, v23, v3
	ds_write2st64_b32 v2, v4, v5 offset0:118 offset1:119
	v_mul_f32_e32 v4, v24, v3
	v_mul_f32_e32 v5, v25, v3
	ds_write2st64_b32 v2, v4, v5 offset0:120 offset1:121
	v_mul_f32_e32 v4, v26, v3
	v_mul_f32_e32 v5, v27, v3
	ds_write2st64_b32 v2, v4, v5 offset0:122 offset1:123
	v_mul_f32_e32 v4, v28, v3
	v_mul_f32_e32 v5, v29, v3
	ds_write2st64_b32 v2, v4, v5 offset0:124 offset1:125
	v_mul_f32_e32 v4, v30, v3
	v_mul_f32_e32 v3, v31, v3
	ds_write2st64_b32 v2, v4, v3 offset0:126 offset1:127
